# unit prologue: four q-row LDS reads issued together; wave max of squared row norms by DPP + permlane swaps instead of six ds_bpermute round trips
# baseline (speedup 1.0000x reference)
.Lpipe_part2:
	s_barrier
	ds_read_b128 v[4:7], v4
	v_bitop3_b32 v10, v9, v8, 1 bitop3:0x36
	v_lshl_add_u32 v10, v10, 4, v3
	ds_read_b128 v[22:25], v10
	v_bitop3_b32 v10, v9, v8, 2 bitop3:0x36
	v_lshl_add_u32 v10, v10, 4, v3
	ds_read_b128 v[26:29], v10
	v_bitop3_b32 v10, v9, v8, 3 bitop3:0x36
	v_lshl_add_u32 v10, v10, 4, v3
	ds_read_b128 v[30:33], v10
	v_cmp_eq_u32_e32 vcc, 0, v19
	s_waitcnt lgkmcnt(3)
	v_lshlrev_b32_e32 v10, 16, v4
	v_and_b32_e32 v4, 0xffff0000, v4
	v_mul_f32_e32 v11, v4, v4
	v_fmac_f32_e32 v11, v10, v10
	v_lshlrev_b32_e32 v4, 16, v5
	v_fmac_f32_e32 v11, v4, v4
	v_and_b32_e32 v4, 0xffff0000, v5
	v_fmac_f32_e32 v11, v4, v4
	v_lshlrev_b32_e32 v4, 16, v6
	v_fmac_f32_e32 v11, v4, v4
	v_and_b32_e32 v4, 0xffff0000, v6
	v_fmac_f32_e32 v11, v4, v4
	v_lshlrev_b32_e32 v4, 16, v7
	v_fmac_f32_e32 v11, v4, v4
	v_and_b32_e32 v4, 0xffff0000, v7
	v_fmac_f32_e32 v11, v4, v4
	s_waitcnt lgkmcnt(2)
	v_lshlrev_b32_e32 v3, 16, v22
	v_fmac_f32_e32 v11, v3, v3
	v_and_b32_e32 v3, 0xffff0000, v22
	v_fmac_f32_e32 v11, v3, v3
	v_lshlrev_b32_e32 v3, 16, v23
	v_fmac_f32_e32 v11, v3, v3
	v_and_b32_e32 v3, 0xffff0000, v23
	v_fmac_f32_e32 v11, v3, v3
	v_lshlrev_b32_e32 v3, 16, v24
	v_fmac_f32_e32 v11, v3, v3
	v_and_b32_e32 v3, 0xffff0000, v24
	v_fmac_f32_e32 v11, v3, v3
	v_lshlrev_b32_e32 v3, 16, v25
	v_fmac_f32_e32 v11, v3, v3
	v_and_b32_e32 v3, 0xffff0000, v25
	v_fmac_f32_e32 v11, v3, v3
	s_waitcnt lgkmcnt(1)
	v_lshlrev_b32_e32 v3, 16, v26
	v_fmac_f32_e32 v11, v3, v3
	v_and_b32_e32 v3, 0xffff0000, v26
	v_fmac_f32_e32 v11, v3, v3
	v_lshlrev_b32_e32 v3, 16, v27
	v_fmac_f32_e32 v11, v3, v3
	v_and_b32_e32 v3, 0xffff0000, v27
	v_fmac_f32_e32 v11, v3, v3
	v_lshlrev_b32_e32 v3, 16, v28
	v_fmac_f32_e32 v11, v3, v3
	v_and_b32_e32 v3, 0xffff0000, v28
	v_fmac_f32_e32 v11, v3, v3
	v_lshlrev_b32_e32 v3, 16, v29
	v_fmac_f32_e32 v11, v3, v3
	v_and_b32_e32 v3, 0xffff0000, v29
	v_fmac_f32_e32 v11, v3, v3
	s_waitcnt lgkmcnt(0)
	v_lshlrev_b32_e32 v3, 16, v30
	v_fmac_f32_e32 v11, v3, v3
	v_and_b32_e32 v3, 0xffff0000, v30
	v_fmac_f32_e32 v11, v3, v3
	v_lshlrev_b32_e32 v3, 16, v31
	v_fmac_f32_e32 v11, v3, v3
	v_and_b32_e32 v3, 0xffff0000, v31
	v_fmac_f32_e32 v11, v3, v3
	v_lshlrev_b32_e32 v3, 16, v32
	v_fmac_f32_e32 v11, v3, v3
	v_and_b32_e32 v3, 0xffff0000, v32
	v_fmac_f32_e32 v11, v3, v3
	v_lshlrev_b32_e32 v3, 16, v33
	v_fmac_f32_e32 v11, v3, v3
	v_and_b32_e32 v3, 0xffff0000, v33
	v_fmac_f32_e32 v11, v3, v3
	s_nop 1
	v_max_f32_dpp v3, v11, v11 row_ror:8 row_mask:0xf bank_mask:0xf
	s_nop 1
	v_max_f32_dpp v3, v3, v3 row_ror:4 row_mask:0xf bank_mask:0xf
	s_nop 1
	v_max_f32_dpp v3, v3, v3 quad_perm:[2,3,0,1] row_mask:0xf bank_mask:0xf
	s_nop 1
	v_max_f32_dpp v3, v3, v3 quad_perm:[1,0,3,2] row_mask:0xf bank_mask:0xf
	v_mov_b32_e32 v4, v3
	s_nop 1
	v_permlane16_swap_b32_e32 v4, v3
	s_nop 0
	v_max_f32_e32 v3, v4, v3
	v_mov_b32_e32 v4, v3
	s_nop 1
	v_permlane32_swap_b32_e32 v4, v3
	s_nop 0
	v_max_f32_e32 v3, v4, v3
	s_and_saveexec_b64 s[4:5], vcc
	s_cbranch_execz .LBB0_300
	v_readlane_b32 s13, v245, 26
	s_nop 3
	v_mov_b32_e32 v4, s13
	ds_write_b32 v4, v3
	v_mov_b32_e32 v246, 0x18080
	v_mov_b32_e32 v247, 0
	ds_write_b32 v246, v247
